# P8 processes its two output-panel rounds in the opposite order (the ACT panels P7 wrote last are read first: still in the Infinity Cache); kn_items spread over all workgroups
# speedup vs baseline: 1.0134x; 1.0068x over previous
; __device__ __forceinline__ void kn_items(Frame& F, int it0, int stride) {
;     const bf16_t* KVM = (const bf16_t*)(F.ws + WS_KVM); bf16_t* KN = (bf16_t*)(F.ws + WS_KN);
;     const int lane = F.lane; const float g0 = F.xkg[2 * lane], g1 = F.xkg[2 * lane + 1];
;     for (int it = it0; it < MM * 4; it += 4 * stride) {
; __global__ void __launch_bounds__(512, 2) layer_fwd(Args args) {
;     ...
;             if (F.bid >= 64) kn_items(F, (F.bid - 64) * 8 + F.wave, (F.G - 64) * 8);
.LBB0_679:


; __device__ __forceinline__ void kn_items(Frame& F, int it0, int stride) {
;     const bf16_t* KVM = (const bf16_t*)(F.ws + WS_KVM); bf16_t* KN = (bf16_t*)(F.ws + WS_KN);
;     const int lane = F.lane; const float g0 = F.xkg[2 * lane], g1 = F.xkg[2 * lane + 1];
;     for (int it = it0; it < MM * 4; it += 4 * stride) {
;         unsigned w[4];
; #pragma unroll
;         for (int j = 0; j < 4; ++j) { const int item = it + j * stride; w[j] = (item < MM * 4) ? *(const unsigned*)(KVM + (size_t)(item >> 2) * 1024 + (item & 3) * 128 + 2 * lane) : 0u; }
;         __builtin_amdgcn_sched_barrier(0);
	v_writelane_b32 v255, s4, 16
	v_writelane_b32 v255, s5, 17
	v_writelane_b32 v255, s6, 18
	v_writelane_b32 v255, s7, 19
	v_writelane_b32 v255, s8, 20
	v_writelane_b32 v255, s9, 21
	v_writelane_b32 v255, s10, 22
	v_writelane_b32 v255, s11, 23
	v_writelane_b32 v255, s12, 24
	v_writelane_b32 v255, s13, 25
	v_writelane_b32 v255, s14, 26
	v_writelane_b32 v255, s15, 27
	v_writelane_b32 v255, s16, 28
	v_writelane_b32 v255, s17, 29
	v_writelane_b32 v255, s18, 30
	v_writelane_b32 v255, s19, 31
	v_writelane_b32 v255, s20, 32
	v_writelane_b32 v255, s21, 33
	v_writelane_b32 v255, s22, 34
	v_writelane_b32 v255, s23, 35
	v_writelane_b32 v255, s24, 36
	v_writelane_b32 v255, s25, 37
	v_writelane_b32 v255, s26, 38
	v_writelane_b32 v255, s27, 39
	v_writelane_b32 v255, s28, 40
	v_writelane_b32 v255, s29, 41
	v_mov_b32_e32 v250, v2
	v_mov_b32_e32 v251, v3
	v_readlane_b32 s0, v254, 53
	v_readlane_b32 s1, v254, 54
	s_lshl_b32 s4, s2, 3
	s_add_i32 s12, s4, s3
	s_add_i32 s4, s12, 0
	s_cmpk_gt_i32 s4, 0x3fff
	s_cbranch_scc1 .Lkn_end
	v_readlane_b32 s16, v254, 0
	v_lshlrev_b32_e32 v0, 3, v208
	v_readlane_b32 s17, v254, 1
	v_mbcnt_lo_u32_b32 v3, -1, 0
	v_mbcnt_hi_u32_b32 v3, -1, v3
	v_and_b32_e32 v4, 64, v3
	v_add_u32_e32 v9, 64, v4
	v_xor_b32_e32 v4, 1, v3
	global_load_dwordx2 v[0:1], v0, s[16:17]
	v_cmp_lt_i32_e32 vcc, v4, v9
	v_xor_b32_e32 v5, 2, v3
	v_xor_b32_e32 v6, 4, v3
	v_cndmask_b32_e32 v4, v3, v4, vcc
	v_cmp_lt_i32_e32 vcc, v5, v9
	v_xor_b32_e32 v7, 8, v3
	v_readlane_b32 s18, v254, 2
	v_cndmask_b32_e32 v5, v3, v5, vcc
	v_cmp_lt_i32_e32 vcc, v6, v9
	v_xor_b32_e32 v8, 16, v3
	s_lshl_b32 s18, s33, 3
	v_cndmask_b32_e32 v6, v3, v6, vcc
	v_cmp_lt_i32_e32 vcc, v7, v9
	v_xor_b32_e32 v10, 32, v3
	v_readlane_b32 s20, v254, 4
	v_cndmask_b32_e32 v7, v3, v7, vcc
	v_cmp_lt_i32_e32 vcc, v8, v9
	s_add_u32 s13, s92, 0x2a00000
	v_readlane_b32 s19, v254, 3
	v_cndmask_b32_e32 v8, v3, v8, vcc
	v_cmp_lt_i32_e32 vcc, v10, v9
	v_readlane_b32 s21, v254, 5
	v_readlane_b32 s22, v254, 6
	v_readlane_b32 s23, v254, 7
	s_addc_u32 s14, s93, 0
	v_lshlrev_b32_e32 v2, 1, v208
	v_cndmask_b32_e32 v3, v3, v10, vcc
	s_lshl_b32 s15, s33, 4
	s_lshl_b32 s16, s33, 5
	s_mul_i32 s17, s33, 24
	s_lshl_b32 s20, s33, 12
	v_lshlrev_b32_e32 v4, 2, v4
	v_lshlrev_b32_e32 v5, 2, v5
	v_lshlrev_b32_e32 v6, 2, v6
	v_lshlrev_b32_e32 v7, 2, v7
	v_lshlrev_b32_e32 v8, 2, v8
	v_lshlrev_b32_e32 v9, 2, v3


; __device__ __forceinline__ void kn_items(Frame& F, int it0, int stride) {
;     ...
;     for (int it = it0; it < MM * 4; it += 4 * stride) {
;         unsigned w[4];
; #pragma unroll
;         for (int j = 0; j < 4; ++j) { const int item = it + j * stride; w[j] = (item < MM * 4) ? *(const unsigned*)(KVM + (size_t)(item >> 2) * 1024 + (item & 3) * 128 + 2 * lane) : 0u; }
;         __builtin_amdgcn_sched_barrier(0);
	s_lshl_b32 s19, s4, 7

; __device__ __forceinline__ void kn_items(Frame& F, int it0, int stride) {
;     ...
;     for (int it = it0; it < MM * 4; it += 4 * stride) {
;         unsigned w[4];
; #pragma unroll
;         for (int j = 0; j < 4; ++j) { const int item = it + j * stride; w[j] = (item < MM * 4) ? *(const unsigned*)(KVM + (size_t)(item >> 2) * 1024 + (item & 3) * 128 + 2 * lane) : 0u; }
;         __builtin_amdgcn_sched_barrier(0);
	v_lshlrev_b32_e32 v10, 1, v2
	s_mov_b32 s21, 0xffff0000
	v_mov_b32_e32 v11, 0x358637bd
	s_mov_b32 s22, 0xf800000
	v_mov_b32_e32 v12, 0x260
	s_movk_i32 s23, 0x7fff
	v_mov_b32_e32 v13, 1
	s_branch .Lkn_612
.Lkn_611:
	s_add_i32 s12, s12, s16
	s_add_i32 s4, s12, 0
	s_add_i32 s19, s19, s20
	s_cmpk_gt_i32 s4, 0x3fff
	s_cbranch_scc1 .Lkn_end
.Lkn_612:
	s_add_i32 s4, s12, 0
	s_ashr_i32 s4, s4, 2
	s_ashr_i32 s5, s4, 31
	s_lshl_b64 s[6:7], s[4:5], 11
	s_add_u32 s6, s0, s6
	s_addc_u32 s7, s1, s7
	s_and_b32 s8, s19, 0x180
	s_lshl_b32 s24, s8, 1
	s_add_u32 s6, s6, s24
	s_addc_u32 s7, s7, 0
	global_load_dword v2, v10, s[6:7]
	s_add_i32 s27, s18, s12
	s_cmpk_lt_i32 s27, 0x4000
	s_cselect_b64 s[10:11], -1, 0
	s_cmpk_gt_i32 s27, 0x3fff
	v_mov_b32_e32 v3, 0
	s_cbranch_scc1 .Lkn_614
	s_ashr_i32 s6, s27, 2
	s_ashr_i32 s7, s6, 31
	s_lshl_b64 s[6:7], s[6:7], 11
	s_add_u32 s6, s0, s6
	s_addc_u32 s7, s1, s7
	s_add_u32 s6, s6, s24
	s_addc_u32 s7, s7, 0
	global_load_dword v3, v10, s[6:7]

;     __device__ __forceinline__ void tile(int L, int& pm, int& pn) const {
;         const unsigned w = (unsigned)(L & 7) * (2u * fnig) + (unsigned)(L >> 3), gid = __umulhi(w, fmagic), rem = w - gid * fnig; pm = (int)(gid * WGM + (rem & 7u)); pn = (int)(rem >> 3);
;     }
; __global__ void __launch_bounds__(512, 2) layer_fwd(Args args) {
;     ...
;     if (IN(8)) {
;         pg8::Sched S; S.A0 = (const char*)(ws + WS_ACT); S.B0 = (const char*)(ws + WS_WDN); S.A1 = S.A0; S.B1 = S.B0;
;         S.nM0 = M / 256; S.nN0 = 4; S.n0 = S.nM0 * 4; S.n1 = 0; S.G = F.G; S.c = vb_; S.tstep = (size_t)256 * FF * 2; S.nrep = NREP(8); S.prep();
;         pg8::EpiAdd E{(const bf16_t*)(ws + WS_HB), F.out, ss3};
;         pg8::gemm_phase<pg8::EpiAdd, true, true>(F.lds, FF, S, E);
.LBB0_1169:
	s_cmp_lt_i32 s82, 9
	s_cselect_b64 s[2:3], -1, 0
	s_and_b64 s[2:3], s[2:3], s[6:7]
	s_andn2_b64 vcc, exec, s[2:3]
	s_cbranch_vccnz .LBB0_1186
	s_cmpk_gt_i32 s52, 0x1ff
	v_readfirstlane_b32 s10, v228
	s_cbranch_scc1 .LBB0_1186
	v_lshrrev_b32_e32 v0, 5, v228
	v_lshrrev_b32_e32 v2, 1, v228
	v_and_b32_e32 v0, 4, v0
	s_waitcnt lgkmcnt(0)
	v_bfe_u32 v1, v228, 2, 2
	v_and_b32_e32 v2, 24, v2
	v_or3_b32 v0, v0, v1, v2
	v_lshlrev_b32_e32 v1, 4, v228
	v_add_u32_e32 v8, 0x2000, v1
	v_lshrrev_b32_e32 v2, 7, v8
	s_movk_i32 s2, 0xe0
	v_and_b32_e32 v4, 32, v228
	v_and_or_b32 v3, v2, s2, v0
	v_bitop3_b32 v9, v1, v4, 48 bitop3:0x6c
	v_and_b32_e32 v10, 64, v228
	v_bfe_u32 v11, v228, 2, 4
	s_movk_i32 s2, 0xf0
	s_add_u32 s28, s92, 0xf000000
	v_or_b32_e32 v1, v9, v10
	v_and_or_b32 v2, v2, s2, v11
	s_addc_u32 s29, s93, 0
	v_lshl_or_b32 v178, v2, 13, v1
	v_lshrrev_b32_e32 v2, 3, v228
	s_movk_i32 s2, 0x60
	s_add_u32 s30, s92, 0x1580000
	v_and_or_b32 v0, v2, s2, v0
	s_movk_i32 s2, 0x70
	s_addc_u32 s31, s93, 0
	v_lshl_or_b32 v180, v0, 13, v1
	v_and_or_b32 v0, v2, s2, v11
	s_lshl_b32 s2, s52, 6
	s_and_b32 s2, s2, 0x1c0
	s_ashr_i32 s3, s52, 3
	s_add_i32 s2, s2, s3
	s_lshr_b32 s2, s2, 2
	s_and_b32 s2, s2, 0x3ffffff8
	s_and_b32 s4, s3, 7
	s_lshr_b32 s8, s10, 6
	s_or_b32 s2, s2, s4
	s_xor_b32 s2, s2, 8
	s_bfe_u32 s45, s3, 0x20003
	s_mov_b32 s3, 0
	s_lshr_b32 s9, s10, 8
	s_lshl_b32 s34, s8, 10
	s_lshl_b64 s[4:5], s[2:3], 21
	s_lshl_b32 s6, s45, 21
	s_add_u32 s24, s30, s6
	s_addc_u32 s25, s31, 0
	s_add_i32 s35, s34, 0
	s_add_i32 m0, s35, 0x10000
	v_lshl_or_b32 v176, v3, 13, v1
	global_load_lds_dwordx4 v180, s[24:25]
	s_add_i32 m0, s35, 0x12000
	s_add_u32 s6, s24, 0x100000
	global_load_lds_dwordx4 v176, s[24:25]
	s_addc_u32 s7, s25, 0
	s_add_i32 m0, s35, 0x14000
	v_lshl_or_b32 v182, v0, 13, v1
	global_load_lds_dwordx4 v180, s[6:7]
	s_add_i32 m0, s35, 0x16000
	s_add_u32 s22, s28, s4
	s_addc_u32 s23, s29, s5
	s_add_i32 s36, s35, 0x2000
	global_load_lds_dwordx4 v176, s[6:7]
	s_mov_b32 m0, s35
	s_add_u32 s4, s22, 0x100000
	global_load_lds_dwordx4 v182, s[22:23]
	s_mov_b32 m0, s36
	s_addc_u32 s5, s23, 0
	s_add_i32 s37, s35, 0x4000
	global_load_lds_dwordx4 v178, s[22:23]
	s_mov_b32 m0, s37
	s_add_i32 s38, s35, 0x6000
	global_load_lds_dwordx4 v182, s[4:5]
	s_mov_b32 m0, s38
	v_mov_b32_e32 v181, 0
	global_load_lds_dwordx4 v178, s[4:5]
	v_mov_b32_e32 v177, v181
	v_mov_b32_e32 v183, v181
	v_mov_b32_e32 v179, v181
	s_cmp_eq_u32 s9, 1
	v_lshl_add_u64 v[6:7], s[24:25], 0, v[180:181]
	v_lshl_add_u64 v[4:5], s[24:25], 0, v[176:177]
	v_lshl_add_u64 v[0:1], s[22:23], 0, v[182:183]
	s_cselect_b64 s[4:5], -1, 0
	s_cmp_lg_u32 s9, 1
	v_lshl_add_u64 v[2:3], s[22:23], 0, v[178:179]
	s_cbranch_scc1 .LBB0_1173
	s_barrier

;     __device__ __forceinline__ void tile(int L, int& pm, int& pn) const {
;         const unsigned w = (unsigned)(L & 7) * (2u * fnig) + (unsigned)(L >> 3), gid = __umulhi(w, fmagic), rem = w - gid * fnig; pm = (int)(gid * WGM + (rem & 7u)); pn = (int)(rem >> 3);
;     }
;     __device__ __forceinline__ bool next(int i, Unit& u) const {
;         int L = i * G + c;
;         if (nrep > 1) { if (L < n0 * nrep) { const int pass = L / n0; tile(L - pass * n0, u.pm, u.pn); u.kind = (pass + 1 < nrep) ? 2 : 0; return true; } L -= n0 * (nrep - 1); }
;         if (L < n0) { tile(L, u.pm, u.pn); u.pn += pnoff; u.kind = 0; return true; }
.LBB0_1176:
	s_add_i32 s3, s3, 1
	s_mul_i32 s13, s3, s33
	s_add_i32 s13, s13, s52
	s_cmpk_lt_i32 s13, 0x200
	s_cselect_b64 s[18:19], -1, 0
	s_cmpk_gt_i32 s13, 0x1ff
	s_cbranch_scc1 .LBB0_1178
	s_lshl_b32 s12, s13, 6
	s_and_b32 s12, s12, 0x1c0
	s_ashr_i32 s13, s13, 3
	s_add_i32 s12, s12, s13
	s_lshr_b32 s12, s12, 2
	s_and_b32 s12, s12, 0x3ffffff8
	s_and_b32 s14, s13, 7
	s_or_b32 s12, s12, s14
	s_xor_b32 s12, s12, 8
	s_bfe_u32 s14, s13, 0x20003
